# up-GEMM epilogue: second column half's conv weights/biases prefetched by LDS-DMA into the idle 16 KB of LDS right after the first half's operands arrive; half-boundary drain replaced by counted vmcnt(
# baseline (speedup 1.0000x reference)
; __device__ __forceinline__ void load_row_scales(const float* ssp, int row0, int fq, float (&rs)[2][4]) {
;     f32x4 part[2][4];
;     const float* sp = ssp + (size_t)row0 * 16 + 4 * fq;
; #pragma unroll
;     for (int ai = 0; ai < 2; ++ai)
; #pragma unroll
;         for (int m = 0; m < 4; ++m) part[ai][m] = *(const f32x4*)(sp + (size_t)(ai * HALF + m * 16) * 16);
; #pragma unroll
;     for (int ai = 0; ai < 2; ++ai)
; #pragma unroll
;         for (int m = 0; m < 4; ++m) { float t = (part[ai][m][0] + part[ai][m][1]) + (part[ai][m][2] + part[ai][m][3]);
;             t += __shfl_xor(t, 16); t += __shfl_xor(t, 32);
;             rs[ai][m] = 1.0f / sqrtf(t * (1.0f / 1024.0f) + 1e-6f); }
;     __device__ __forceinline__ void operator()(f32x4 (&acc)[2][2][4][2], const Unit& u, int wr, int wc, int fr, int fq) const {
;     ...
;         for (int n = 0; n < 2; ++n) {
;             const int gc0 = u.pn * 128 + wc * 32 + 8 * fq + 4 * n;
;             const float* cwp = cw + gc0; asm volatile("" : "+v"(cwp));
;             const f32x4 wg0 = *(const f32x4*)(cwp), wg1 = *(const f32x4*)(cwp + FF2c), wg2 = *(const f32x4*)(cwp + 2 * FF2c);
;             const f32x4 wv0 = *(const f32x4*)(cwp + FFc), wv1 = *(const f32x4*)(cwp + FF2c + FFc), wv2 = *(const f32x4*)(cwp + 2 * FF2c + FFc);
;             const f32x4 bg = *(const f32x4*)(cb + gc0), bv = *(const f32x4*)(cb + FFc + gc0);
;             bf16_t* gp = G + (size_t)row0 * FFc + gc0;
;             bf16_t* sb = Fb + ((size_t)(row0 >> 6) * 2 + (fr & 1)) * FF2c + gc0;
;             bf16_t* hb = Hb + ((size_t)(row0 >> 6) * 2 + (fr & 1)) * FF2c + gc0;
; #pragma unroll
;             for (int ai = 0; ai < 2; ++ai) {
; #pragma unroll
;                 for (int m = 0; m < 4; ++m) {
;                     float og[4];
; #pragma unroll
;                     for (int j = 0; j < 4; ++j) {
;                         const float vg = acc[ai][0][m][n][j], vv = acc[ai][1][m][n][j];
;                         const float pg = (m > 0) ? acc[ai][0][m - 1][n][j] : 0.f, pv = (m > 0) ? acc[ai][1][m - 1][n][j] : 0.f;
;                         const float g1 = dppf(dppf(0.f, pg, 2), vg, 0), g2 = dppf(dppf(0.f, pg, 3), vg, 1);
;                         const float v1 = dppf(dppf(0.f, pv, 2), vv, 0), v2 = dppf(dppf(0.f, pv, 3), vv, 1);
.LBB0_1350:
	s_lshl_b32 s13, s13, 8
	s_add_i32 s13, s13, s24
	v_or_b32_e32 v176, s13, v161
	v_ashrrev_i32_e32 v177, 31, v176
	v_lshlrev_b64 v[130:131], 6, v[176:177]
	v_lshl_add_u64 v[146:147], v[162:163], 0, v[130:131]
	global_load_dwordx4 v[130:133], v[146:147], off
	global_load_dwordx4 v[134:137], v[146:147], off offset:1024
	global_load_dwordx4 v[138:141], v[146:147], off offset:2048
	global_load_dwordx4 v[142:145], v[146:147], off offset:3072
	v_add_co_u32_e32 v168, vcc, 0x2000, v146
	v_mov_b32_e32 v177, v1
	s_nop 0
	v_addc_co_u32_e32 v169, vcc, 0, v147, vcc
	global_load_dwordx4 v[146:149], v[168:169], off
	global_load_dwordx4 v[150:153], v[168:169], off offset:1024
	global_load_dwordx4 v[170:173], v[168:169], off offset:2048
	global_load_dwordx4 v[178:181], v[168:169], off offset:3072
	v_and_b32_e32 v169, 64, v229
	v_xor_b32_e32 v168, 16, v229
	v_add_u32_e32 v169, 64, v169
	v_cmp_lt_i32_e32 vcc, v168, v169
	v_mov_b32_dpp v177, v177 row_ror:1 row_mask:0xf bank_mask:0xf
	v_mov_b32_e32 v189, v177
	v_cndmask_b32_e32 v168, v229, v168, vcc
	v_lshlrev_b32_e32 v174, 2, v168
	v_xor_b32_e32 v168, 32, v229
	v_cmp_lt_i32_e32 vcc, v168, v169
	s_waitcnt vmcnt(0)
	s_mov_b32 s100, 1
	v_mov_b32_e32 v169, v132
	v_cndmask_b32_e32 v168, v229, v168, vcc
	v_lshlrev_b32_e32 v175, 2, v168
	v_mov_b32_e32 v168, v131
	v_mov_b32_e32 v131, v133
	v_pk_add_f32 v[130:131], v[168:169], v[130:131]
	s_nop 0
	v_add_f32_e32 v130, v130, v131
	v_mov_b32_e32 v131, v130
	s_nop 1
	v_permlane16_swap_b32_e32 v131, v130
	s_waitcnt lgkmcnt(0)
	v_add_f32_e32 v130, v130, v131
	v_mov_b32_e32 v131, v130
	s_nop 1
	v_permlane32_swap_b32_e32 v131, v130
	s_waitcnt lgkmcnt(0)
	v_add_f32_e32 v130, v130, v131
	v_fmamk_f32 v130, v130, 0x3a800000, v230
	s_ashr_i32 s0, s13, 5
	v_rsq_f32_e32 v168, v130
	s_nop 0
	v_mov_b32_e32 v130, v135
	v_mov_b32_e32 v131, v136
	v_mov_b32_e32 v135, v137
	v_pk_add_f32 v[130:131], v[130:131], v[134:135]
	s_nop 0
	v_add_f32_e32 v130, v130, v131
	v_mov_b32_e32 v131, v130
	s_nop 1
	v_permlane16_swap_b32_e32 v131, v130
	s_waitcnt lgkmcnt(0)
	v_add_f32_e32 v205, v130, v131
	v_mov_b32_e32 v130, v139
	v_mov_b32_e32 v131, v140
	v_mov_b32_e32 v139, v141
	v_pk_add_f32 v[130:131], v[130:131], v[138:139]
	ds_bpermute_b32 v206, v175, v205
	v_add_f32_e32 v130, v130, v131
	v_mov_b32_e32 v131, v130
	s_nop 1
	v_permlane16_swap_b32_e32 v131, v130
	s_waitcnt lgkmcnt(0)
	v_add_f32_e32 v203, v130, v131
	v_mov_b32_e32 v130, v143
	v_mov_b32_e32 v131, v144
	v_mov_b32_e32 v143, v145
	v_pk_add_f32 v[130:131], v[130:131], v[142:143]
	ds_bpermute_b32 v204, v175, v203
	v_add_f32_e32 v130, v130, v131
	v_mov_b32_e32 v131, v130
	s_nop 1
	v_permlane16_swap_b32_e32 v131, v130
	s_waitcnt lgkmcnt(0)
	v_add_f32_e32 v182, v130, v131
	v_mov_b32_e32 v130, v147
	v_mov_b32_e32 v131, v148
	v_mov_b32_e32 v147, v149
	v_pk_add_f32 v[130:131], v[130:131], v[146:147]
	ds_bpermute_b32 v202, v175, v182
	v_add_f32_e32 v130, v130, v131
	v_mov_b32_e32 v131, v130
	s_nop 1
	v_permlane16_swap_b32_e32 v131, v130
	s_waitcnt lgkmcnt(0)
	v_add_f32_e32 v244, v130, v131
	v_mov_b32_e32 v130, v151
	v_mov_b32_e32 v131, v152
	v_mov_b32_e32 v151, v153
	v_pk_add_f32 v[130:131], v[130:131], v[150:151]
	ds_bpermute_b32 v245, v175, v244
	v_add_f32_e32 v130, v130, v131
	v_mov_b32_e32 v131, v130
	s_nop 1
	v_permlane16_swap_b32_e32 v131, v130
	s_waitcnt lgkmcnt(0)
	v_add_f32_e32 v242, v130, v131
	v_mov_b32_e32 v130, v171
	v_mov_b32_e32 v131, v172
	v_mov_b32_e32 v171, v173
	v_pk_add_f32 v[130:131], v[130:131], v[170:171]
	v_lshl_or_b32 v170, s12, 7, v238
	v_add_f32_e32 v130, v130, v131
	v_mov_b32_e32 v131, v130
	s_nop 1
	v_permlane16_swap_b32_e32 v131, v130
	v_ashrrev_i32_e32 v171, 31, v170
	v_lshlrev_b64 v[150:151], 2, v[170:171]
	v_lshl_add_u64 v[172:173], s[70:71], 0, v[150:151]
	ds_bpermute_b32 v243, v175, v242
	s_waitcnt lgkmcnt(0)
	v_add_f32_e32 v240, v130, v131
	v_mov_b32_e32 v130, v179
	v_mov_b32_e32 v131, v180
	v_mov_b32_e32 v179, v181
	v_pk_add_f32 v[130:131], v[130:131], v[178:179]
	ds_bpermute_b32 v241, v175, v240
	v_add_f32_e32 v130, v130, v131
	v_mov_b32_e32 v131, v130
	s_nop 1
	v_permlane16_swap_b32_e32 v131, v130
	v_lshlrev_b64 v[178:179], 1, v[170:171]
	s_waitcnt lgkmcnt(0)
	v_add_f32_e32 v169, v130, v131
	v_pk_mul_f32 v[196:197], v[98:99], v[168:169] op_sel_hi:[1,0]
	v_or_b32_e32 v98, s0, v160
	v_mad_i64_i32 v[200:201], s[0:1], v98, s37, 0
	v_pk_mul_f32 v[198:199], v[102:103], v[168:169] op_sel_hi:[1,0]
	v_mov_b64_e32 v[102:103], v[172:173]
	s_movk_i32 s0, 0x5000
	ds_bpermute_b32 v183, v175, v169
	v_add_co_u32_e32 v98, vcc, s0, v102
	s_mov_b32 s0, 0xb000
	s_nop 0
	v_addc_co_u32_e32 v99, vcc, 0, v103, vcc
	global_load_dwordx4 v[142:145], v[98:99], off offset:2048
	v_add_co_u32_e32 v98, vcc, s0, v102
	s_movk_i32 s0, 0x2000
	s_nop 0
	v_addc_co_u32_e32 v99, vcc, 0, v103, vcc
	v_pk_mul_f32 v[194:195], v[104:105], v[168:169] op_sel_hi:[1,0]
	v_add_co_u32_e32 v104, vcc, s0, v102
	v_lshl_add_u64 v[174:175], s[72:73], 0, v[150:151]
	global_load_dwordx4 v[138:141], v[102:103], off
	v_addc_co_u32_e32 v105, vcc, 0, v103, vcc
	s_mov_b32 s0, 0x8000
	global_load_dwordx4 v[146:149], v[174:175], off
	global_load_dwordx4 v[130:133], v[104:105], off offset:3072
	v_add_co_u32_e32 v104, vcc, s0, v102
	v_lshl_add_u64 v[150:151], s[76:77], 0, v[150:151]
	v_pk_mul_f32 v[192:193], v[100:101], v[168:169] op_sel_hi:[1,0]
	global_load_dwordx4 v[98:101], v[98:99], off
	v_addc_co_u32_e32 v105, vcc, 0, v103, vcc
	global_load_dwordx4 v[150:153], v[150:151], off
	s_mov_b32 s0, 0xd000
	global_load_dwordx4 v[134:137], v[104:105], off offset:1024
	v_add_co_u32_e32 v102, vcc, s0, v102
	v_readlane_b32 s0, v253, 44
	s_nop 0
	v_addc_co_u32_e32 v103, vcc, 0, v103, vcc
	global_load_dwordx4 v[102:105], v[102:103], off offset:3072
	v_readlane_b32 s1, v253, 45
	v_mov_b32_dpp v189, v196 row_shr:1 row_mask:0xf bank_mask:0xf
	s_nop 0
	v_lshl_add_u64 v[180:181], v[200:201], 1, s[0:1]
	v_lshl_add_u64 v[184:185], v[180:181], 0, v[178:179]
	v_mov_b32_e32 v181, v1
	v_mov_b32_e32 v180, v177
	s_nop 0
	v_mov_b32_dpp v181, v181 row_ror:2 row_mask:0xf bank_mask:0xf
	v_mov_b32_e32 v188, v181
	v_mov_b32_dpp v180, v198 row_shr:1 row_mask:0xf bank_mask:0xf
	v_mov_b32_e32 v190, v181
	v_mov_b32_dpp v188, v198 row_shr:2 row_mask:0xf bank_mask:0xf
	v_mov_b32_e32 v191, v181
	v_mov_b32_dpp v190, v196 row_shr:2 row_mask:0xf bank_mask:0xf
	v_mov_b32_e32 v207, v181
	v_mov_b32_dpp v191, v197 row_shr:2 row_mask:0xf bank_mask:0xf
	s_waitcnt vmcnt(0) lgkmcnt(0)
;     __device__ __forceinline__ void operator()(f32x4 (&acc)[2][2][4][2], const Unit& u, int wr, int wc, int fr, int fq) const {
;     ...
;         for (int n = 0; n < 2; ++n) {
;             const int gc0 = u.pn * 128 + wc * 32 + 8 * fq + 4 * n;
;             const float* cwp = cw + gc0; asm volatile("" : "+v"(cwp));
;             const f32x4 wg0 = *(const f32x4*)(cwp), wg1 = *(const f32x4*)(cwp + FF2c), wg2 = *(const f32x4*)(cwp + 2 * FF2c);
;             const f32x4 wv0 = *(const f32x4*)(cwp + FFc), wv1 = *(const f32x4*)(cwp + FF2c + FFc), wv2 = *(const f32x4*)(cwp + 2 * FF2c + FFc);
;             const f32x4 bg = *(const f32x4*)(cb + gc0), bv = *(const f32x4*)(cb + FFc + gc0);
;     ...
; #pragma unroll
;             for (int ai = 0; ai < 2; ++ai) {
; #pragma unroll
;                 for (int m = 0; m < 4; ++m) {
;                     float og[4];
; #pragma unroll
;                     for (int j = 0; j < 4; ++j) {
;                         const float vg = acc[ai][0][m][n][j], vv = acc[ai][1][m][n][j];
;                         const float pg = (m > 0) ? acc[ai][0][m - 1][n][j] : 0.f, pv = (m > 0) ? acc[ai][1][m - 1][n][j] : 0.f;
;                         const float g1 = dppf(dppf(0.f, pg, 2), vg, 0), g2 = dppf(dppf(0.f, pg, 3), vg, 1);
;                         const float v1 = dppf(dppf(0.f, pv, 2), vv, 0), v2 = dppf(dppf(0.f, pv, 3), vv, 1);
;                         const float cgate = bg[j] + wg0[j] * g2 + wg1[j] * g1 + wg2[j] * vg;
;                         const float cval = bv[j] + wv0[j] * v2 + wv1[j] * v1 + wv2[j] * vv;
;                         og[j] = cgate * __builtin_amdgcn_rcpf(1.0f + __builtin_amdgcn_exp2f(-1.4426950408889634f * cgate)) * cval; }
;                     const unsigned long long w = (unsigned long long)cvt_pk_bf16(og[0], og[1]) | ((unsigned long long)cvt_pk_bf16(og[2], og[3]) << 32);
;                     if (m == 0) {
;                         if (fr >= 2) *(unsigned long long*)gp = w;
;                         else { *(unsigned long long*)sb = (unsigned long long)cvt_pk_bf16(acc[ai][0][0][n][0], acc[ai][0][0][n][1]) | ((unsigned long long)cvt_pk_bf16(acc[ai][0][0][n][2], acc[ai][0][0][n][3]) << 32);
;                                *(unsigned long long*)(sb + FFc) = (unsigned long long)cvt_pk_bf16(acc[ai][1][0][n][0], acc[ai][1][0][n][1]) | ((unsigned long long)cvt_pk_bf16(acc[ai][1][0][n][2], acc[ai][1][0][n][3]) << 32); }
	v_mbcnt_lo_u32_b32 v231, -1, 0
	v_mbcnt_hi_u32_b32 v231, -1, v231
	v_lshrrev_b32_e32 v231, 4, v231
	v_lshl_add_u32 v231, v231, 8, s96
	v_add_u32_e32 v231, 0x20000, v231
	s_mov_b32 exec_lo, 0x10001
	s_mov_b32 exec_hi, 0x10001
	s_nop 1
	v_lshl_add_u64 v[220:221], v[172:173], 0, 16
	v_mov_b32_e32 v223, 0
	s_add_i32 m0, s96, 0x20000
	s_nop 0
	global_load_lds_dwordx4 v[220:221], off
	v_mov_b32_e32 v222, 0x5800
	s_add_i32 m0, s96, 0x20010
	v_lshl_add_u64 v[226:227], v[220:221], 0, v[222:223]
	global_load_lds_dwordx4 v[226:227], off
	v_mov_b32_e32 v222, 0xb000
	s_add_i32 m0, s96, 0x20020
	v_lshl_add_u64 v[224:225], v[220:221], 0, v[222:223]
	global_load_lds_dwordx4 v[224:225], off
	v_mov_b32_e32 v222, 0x2c00
	s_add_i32 m0, s96, 0x20030
	v_lshl_add_u64 v[226:227], v[220:221], 0, v[222:223]
	global_load_lds_dwordx4 v[226:227], off
	v_mov_b32_e32 v222, 0x8400
	s_add_i32 m0, s96, 0x20040
	v_lshl_add_u64 v[224:225], v[220:221], 0, v[222:223]
	global_load_lds_dwordx4 v[224:225], off
	v_mov_b32_e32 v222, 0xdc00
	s_add_i32 m0, s96, 0x20050
	v_lshl_add_u64 v[226:227], v[220:221], 0, v[222:223]
	global_load_lds_dwordx4 v[226:227], off
	s_add_i32 m0, s96, 0x20060
	v_lshl_add_u64 v[224:225], v[174:175], 0, 16
	global_load_lds_dwordx4 v[224:225], off
	v_or_b32_e32 v226, 4, v170
	s_add_i32 m0, s96, 0x20070
	v_ashrrev_i32_e32 v227, 31, v226
	v_lshl_add_u64 v[226:227], v[226:227], 2, s[76:77]
	global_load_lds_dwordx4 v[226:227], off
	s_mov_b64 exec, -1
	s_nop 1
	v_fma_f32 v188, v138, v188, v146
	v_fmac_f32_e32 v188, v142, v180
	v_mov_b32_dpp v207, v192 row_shr:2 row_mask:0xf bank_mask:0xf
	v_fmac_f32_e32 v188, v198, v98
	v_fma_f32 v180, v130, v190, v150
	v_mov_b32_e32 v190, v177
	v_fmac_f32_e32 v180, v134, v189
	v_mul_f32_e32 v189, 0xbfb8aa3b, v188
	v_exp_f32_e32 v189, v189
	v_mov_b32_dpp v190, v197 row_shr:1 row_mask:0xf bank_mask:0xf
	v_add_f32_e32 v189, 1.0, v189
	v_rcp_f32_e32 v189, v189
	v_fmac_f32_e32 v180, v196, v102
	v_mul_f32_e32 v188, v188, v189
	v_mov_b32_e32 v189, v181
	v_mul_f32_e32 v180, v180, v188
	v_mov_b32_e32 v188, v177
	v_mov_b32_dpp v189, v199 row_shr:2 row_mask:0xf bank_mask:0xf
	v_fma_f32 v189, v139, v189, v147
	v_mov_b32_dpp v188, v199 row_shr:1 row_mask:0xf bank_mask:0xf
	v_fmac_f32_e32 v189, v143, v188
	v_fmac_f32_e32 v189, v199, v99
	v_fma_f32 v188, v131, v191, v151
	v_fmac_f32_e32 v188, v135, v190
	v_mul_f32_e32 v190, 0xbfb8aa3b, v189
	v_exp_f32_e32 v190, v190
	v_fmac_f32_e32 v188, v197, v103
	v_mov_b32_e32 v191, v177
	v_add_f32_e32 v190, 1.0, v190
	v_rcp_f32_e32 v190, v190
	v_mov_b32_dpp v191, v192 row_shr:1 row_mask:0xf bank_mask:0xf
	v_mul_f32_e32 v189, v189, v190
	v_mov_b32_e32 v190, v181
	v_mul_f32_e32 v188, v188, v189
	v_mov_b32_e32 v189, v177
	v_mov_b32_dpp v190, v194 row_shr:2 row_mask:0xf bank_mask:0xf
	v_fma_f32 v190, v140, v190, v148
	v_mov_b32_dpp v189, v194 row_shr:1 row_mask:0xf bank_mask:0xf
	v_fmac_f32_e32 v190, v144, v189
	v_fmac_f32_e32 v190, v194, v100
	v_fma_f32 v189, v132, v207, v152
	v_fmac_f32_e32 v189, v136, v191
	v_mul_f32_e32 v191, 0xbfb8aa3b, v190
	v_exp_f32_e32 v191, v191
	v_fmac_f32_e32 v189, v192, v104
	v_cvt_pk_bf16_f32 v180, v180, v188
	v_add_f32_e32 v191, 1.0, v191
	v_rcp_f32_e32 v191, v191
	s_nop 0
	v_mul_f32_e32 v190, v190, v191
	v_mov_b32_e32 v191, v181
	v_mul_f32_e32 v189, v189, v190
	v_mov_b32_e32 v190, v177
	v_mov_b32_dpp v191, v195 row_shr:2 row_mask:0xf bank_mask:0xf
	v_fma_f32 v191, v141, v191, v149
	v_mov_b32_dpp v190, v195 row_shr:1 row_mask:0xf bank_mask:0xf
	v_mov_b32_dpp v181, v193 row_shr:2 row_mask:0xf bank_mask:0xf
	v_fmac_f32_e32 v191, v145, v190
	v_mov_b32_dpp v177, v193 row_shr:1 row_mask:0xf bank_mask:0xf
	v_fmac_f32_e32 v191, v195, v101
	v_fma_f32 v181, v133, v181, v153
	v_fmac_f32_e32 v181, v137, v177
	v_mul_f32_e32 v177, 0xbfb8aa3b, v191
	v_exp_f32_e32 v177, v177
	v_fmac_f32_e32 v181, v193, v105
	v_add_f32_e32 v177, 1.0, v177
	v_rcp_f32_e32 v177, v177
	s_nop 0
	v_mul_f32_e32 v177, v191, v177
	v_mul_f32_e32 v177, v181, v177
	v_cvt_pk_bf16_f32 v181, v189, v177
	s_and_saveexec_b64 s[0:1], s[6:7]
	s_xor_b64 s[0:1], exec, s[0:1]
	s_mov_b64 s[50:51], 0x16000
	s_mov_b64 s[52:53], 0x58000
	s_mov_b64 s[54:55], 0xb000
	s_cbranch_execz .LBB0_1352
	v_cvt_pk_bf16_f32 v180, v198, v199
	v_cvt_pk_bf16_f32 v181, v194, v195
	v_add_co_u32_e32 v188, vcc, 0x1000, v184
	global_store_dwordx2 v[184:185], v[180:181], off
	v_cvt_pk_bf16_f32 v180, v196, v197
	v_cvt_pk_bf16_f32 v181, v192, v193
	s_nop 0
	v_addc_co_u32_e32 v189, vcc, 0, v185, vcc
	global_store_dwordx2 v[188:189], v[180:181], off offset:1536

;     __device__ __forceinline__ void operator()(f32x4 (&acc)[2][2][4][2], const Unit& u, int wr, int wc, int fr, int fq) const {
;     ...
;         for (int n = 0; n < 2; ++n) {
;             const int gc0 = u.pn * 128 + wc * 32 + 8 * fq + 4 * n;
;             const float* cwp = cw + gc0; asm volatile("" : "+v"(cwp));
;             const f32x4 wg0 = *(const f32x4*)(cwp), wg1 = *(const f32x4*)(cwp + FF2c), wg2 = *(const f32x4*)(cwp + 2 * FF2c);
;             const f32x4 wv0 = *(const f32x4*)(cwp + FFc), wv1 = *(const f32x4*)(cwp + FF2c + FFc), wv2 = *(const f32x4*)(cwp + 2 * FF2c + FFc);
;             const f32x4 bg = *(const f32x4*)(cb + gc0), bv = *(const f32x4*)(cb + FFc + gc0);
;             bf16_t* gp = G + (size_t)row0 * FFc + gc0;
;             bf16_t* sb = Fb + ((size_t)(row0 >> 6) * 2 + (fr & 1)) * FF2c + gc0;
;             bf16_t* hb = Hb + ((size_t)(row0 >> 6) * 2 + (fr & 1)) * FF2c + gc0;
; #pragma unroll
;             for (int ai = 0; ai < 2; ++ai) {
; #pragma unroll
;                 for (int m = 0; m < 4; ++m) {
;                     float og[4];
; #pragma unroll
;                     for (int j = 0; j < 4; ++j) {
;                         const float vg = acc[ai][0][m][n][j], vv = acc[ai][1][m][n][j];
;                         const float pg = (m > 0) ? acc[ai][0][m - 1][n][j] : 0.f, pv = (m > 0) ? acc[ai][1][m - 1][n][j] : 0.f;
;                         const float g1 = dppf(dppf(0.f, pg, 2), vg, 0), g2 = dppf(dppf(0.f, pg, 3), vg, 1);
;                         const float v1 = dppf(dppf(0.f, pv, 2), vv, 0), v2 = dppf(dppf(0.f, pv, 3), vv, 1);
;                         const float cgate = bg[j] + wg0[j] * g2 + wg1[j] * g1 + wg2[j] * vg;
;                         const float cval = bv[j] + wv0[j] * v2 + wv1[j] * v1 + wv2[j] * vv;
;                         og[j] = cgate * __builtin_amdgcn_rcpf(1.0f + __builtin_amdgcn_exp2f(-1.4426950408889634f * cgate)) * cval; }
.LBB0_1362:
	s_or_b64 exec, exec, s[0:1]
	v_mov_b32_e32 v169, v168
	v_pk_mul_f32 v[102:103], v[58:59], v[168:169]
	v_lshl_add_u64 v[58:59], v[74:75], 0, s[50:51]
	v_mov_b32_e32 v66, v168
	v_mov_b32_e32 v67, v168
	v_pk_mul_f32 v[104:105], v[62:63], v[168:169]
	v_pk_mul_f32 v[98:99], v[60:61], v[66:67]
	v_lshl_add_u64 v[58:59], v[58:59], 0, s[52:53]
	v_lshl_add_u64 v[60:61], v[96:97], 0, s[54:55]
	v_lshl_add_u64 v[62:63], v[204:205], 0, s[54:55]
	v_lshl_add_u64 v[78:79], v[172:173], 0, 16
	s_movk_i32 s0, 0x5000
	v_pk_mul_f32 v[100:101], v[64:65], v[66:67]
	v_add_co_u32_e32 v62, vcc, s0, v78
	s_mov_b32 s0, 0xb000
	s_nop 0
	v_addc_co_u32_e32 v63, vcc, 0, v79, vcc
	s_waitcnt vmcnt(6)
	ds_read_b128 v[66:69], v231 offset:16
	v_add_co_u32_e32 v62, vcc, s0, v78
	s_movk_i32 s0, 0x2000
	s_nop 0
	v_addc_co_u32_e32 v63, vcc, 0, v79, vcc
	ds_read_b128 v[58:61], v231
	ds_read_b128 v[74:77], v231 offset:32
	v_add_co_u32_e32 v62, vcc, s0, v78
	s_mov_b32 s0, 0x8000
	s_nop 0
	v_addc_co_u32_e32 v63, vcc, 0, v79, vcc
	v_add_co_u32_e32 v70, vcc, s0, v78
	s_mov_b32 s0, 0xd000
	s_nop 0
	v_addc_co_u32_e32 v71, vcc, 0, v79, vcc
	v_add_co_u32_e32 v78, vcc, s0, v78
	v_or_b32_e32 v86, 4, v170
	s_nop 0
	v_addc_co_u32_e32 v79, vcc, 0, v79, vcc
	v_ashrrev_i32_e32 v87, 31, v86
	ds_read_b128 v[62:65], v231 offset:48
	v_lshl_add_u64 v[86:87], v[86:87], 2, s[76:77]
	ds_read_b128 v[70:73], v231 offset:64
	s_nop 0
	ds_read_b128 v[78:81], v231 offset:80
	s_nop 0
	ds_read_b128 v[82:85], v231 offset:96
	v_mov_b32_e32 v95, v1
	ds_read_b128 v[86:89], v231 offset:112
	v_mov_b32_e32 v91, v1
	v_mov_b32_dpp v95, v95 row_ror:2 row_mask:0xf bank_mask:0xf
	v_mov_b32_e32 v107, v95
	v_mov_b32_dpp v91, v91 row_ror:1 row_mask:0xf bank_mask:0xf
	v_mov_b32_e32 v93, v91
	v_mov_b32_dpp v107, v104 row_shr:2 row_mask:0xf bank_mask:0xf
	v_mov_b32_e32 v111, v95
	v_mov_b32_dpp v93, v104 row_shr:1 row_mask:0xf bank_mask:0xf
	v_mov_b32_e32 v110, v91
	v_mov_b32_dpp v111, v102 row_shr:2 row_mask:0xf bank_mask:0xf
	v_mov_b32_e32 v112, v95
	v_mov_b32_dpp v110, v102 row_shr:1 row_mask:0xf bank_mask:0xf
	v_mov_b32_e32 v113, v95
	v_mov_b32_dpp v112, v103 row_shr:2 row_mask:0xf bank_mask:0xf
	v_lshl_add_u64 v[96:97], v[184:185], 0, 8
	v_mov_b32_dpp v113, v98 row_shr:2 row_mask:0xf bank_mask:0xf
	s_waitcnt lgkmcnt(0)
	v_fma_f32 v107, v58, v107, v82
	v_fmac_f32_e32 v107, v66, v93
	v_fmac_f32_e32 v107, v104, v74
	v_fma_f32 v93, v62, v111, v86
	v_fmac_f32_e32 v93, v70, v110
	v_mul_f32_e32 v110, 0xbfb8aa3b, v107
	v_exp_f32_e32 v110, v110
	v_fmac_f32_e32 v93, v102, v78
	v_mov_b32_e32 v111, v91
	v_add_f32_e32 v110, 1.0, v110
	v_rcp_f32_e32 v110, v110
	v_mov_b32_dpp v111, v103 row_shr:1 row_mask:0xf bank_mask:0xf
	v_mul_f32_e32 v107, v107, v110
	v_mov_b32_e32 v110, v95
	v_mul_f32_e32 v93, v93, v107
	v_mov_b32_e32 v107, v91
	v_mov_b32_dpp v110, v105 row_shr:2 row_mask:0xf bank_mask:0xf
	v_fma_f32 v110, v59, v110, v83
	v_mov_b32_dpp v107, v105 row_shr:1 row_mask:0xf bank_mask:0xf
	v_fmac_f32_e32 v110, v67, v107
	v_fmac_f32_e32 v110, v105, v75
	v_fma_f32 v107, v63, v112, v87
	v_fmac_f32_e32 v107, v71, v111
	v_mul_f32_e32 v111, 0xbfb8aa3b, v110
	v_exp_f32_e32 v111, v111
	v_fmac_f32_e32 v107, v103, v79
	v_mov_b32_e32 v112, v91
	v_add_f32_e32 v111, 1.0, v111
	v_rcp_f32_e32 v111, v111
	v_mov_b32_dpp v112, v98 row_shr:1 row_mask:0xf bank_mask:0xf
	v_mul_f32_e32 v110, v110, v111
	v_mov_b32_e32 v111, v95
	v_mul_f32_e32 v107, v107, v110
	v_mov_b32_e32 v110, v91
	v_mov_b32_dpp v111, v100 row_shr:2 row_mask:0xf bank_mask:0xf
	v_fma_f32 v111, v60, v111, v84
	v_mov_b32_dpp v110, v100 row_shr:1 row_mask:0xf bank_mask:0xf
	v_fmac_f32_e32 v111, v68, v110
	v_fmac_f32_e32 v111, v100, v76
	v_fma_f32 v110, v64, v113, v88
	v_fmac_f32_e32 v110, v72, v112
	v_mul_f32_e32 v112, 0xbfb8aa3b, v111
	v_exp_f32_e32 v112, v112
	v_fmac_f32_e32 v110, v98, v80
	v_add_f32_e32 v112, 1.0, v112
	v_rcp_f32_e32 v112, v112
	s_nop 0
	v_mul_f32_e32 v111, v111, v112
	v_mov_b32_e32 v112, v95
	v_mul_f32_e32 v111, v110, v111
	v_mov_b32_e32 v110, v91
	v_mov_b32_dpp v112, v101 row_shr:2 row_mask:0xf bank_mask:0xf
	v_fma_f32 v112, v61, v112, v85
	v_mov_b32_dpp v110, v101 row_shr:1 row_mask:0xf bank_mask:0xf
	v_mov_b32_dpp v95, v99 row_shr:2 row_mask:0xf bank_mask:0xf
	v_fmac_f32_e32 v112, v69, v110
	v_mov_b32_dpp v91, v99 row_shr:1 row_mask:0xf bank_mask:0xf
	v_fmac_f32_e32 v112, v101, v77
	v_fma_f32 v95, v65, v95, v89
	v_fmac_f32_e32 v95, v73, v91
	v_mul_f32_e32 v91, 0xbfb8aa3b, v112
	v_exp_f32_e32 v91, v91
	v_fmac_f32_e32 v95, v99, v81
	v_cvt_pk_bf16_f32 v110, v93, v107
	v_add_f32_e32 v91, 1.0, v91
	v_rcp_f32_e32 v91, v91
	s_nop 0
	v_mul_f32_e32 v91, v112, v91
	v_mul_f32_e32 v91, v95, v91
	v_cvt_pk_bf16_f32 v111, v111, v91
	s_and_saveexec_b64 s[0:1], s[6:7]
	s_xor_b64 s[0:1], exec, s[0:1]
	s_cbranch_execz .LBB0_1364
	v_cvt_pk_bf16_f32 v110, v104, v105
	v_cvt_pk_bf16_f32 v111, v100, v101
	v_add_co_u32_e32 v112, vcc, 0x1000, v96
	global_store_dwordx2 v[96:97], v[110:111], off
	v_cvt_pk_bf16_f32 v110, v102, v103
	v_cvt_pk_bf16_f32 v111, v98, v99
	s_nop 0
	v_addc_co_u32_e32 v113, vcc, 0, v97, vcc
	global_store_dwordx2 v[112:113], v[110:111], off offset:1536
